# G1: straight-line epilogue for the raw and x0.125 column tiles (15 of 31), bypassing the per-piece mode switch of the generic epilogue
# speedup vs baseline: 1.0004x; 1.0004x over previous
.LBB0_812:
	s_cmp_eq_u32 s3, 0
	s_cbranch_scc1 .Lg1_fast
	s_cmp_eq_u32 s3, 2
	s_cbranch_scc1 .Lg1_fast
	s_cmp_eq_u32 s3, 3
	v_lshl_or_b32 v162, s56, 8, v176
	s_cselect_b64 s[26:27], -1, 0
	s_cmp_lg_u32 s3, 3
	s_cselect_b64 s[24:25], -1, 0
	v_ashrrev_i32_e32 v163, 31, v162
	v_lshl_add_u64 v[164:165], v[162:163], 2, s[22:23]
	v_mov_b32_e32 v42, 0
	s_and_b64 vcc, exec, s[24:25]
	v_mov_b32_e32 v46, 0
	v_mov_b32_e32 v47, 0
	v_mov_b32_e32 v48, 0
	v_mov_b32_e32 v49, 0
	s_cbranch_vccnz .LBB0_814
	v_add_co_u32_e32 v26, vcc, 0xffffc000, v164
	s_nop 1
	v_addc_co_u32_e32 v27, vcc, -1, v165, vcc
	global_load_dwordx4 v[46:49], v[26:27], off offset:-3072

.Lg1_fast:
	v_lshl_or_b32 v162, s56, 8, v176
	v_lshl_add_u32 v0, s2, 8, v174
	s_movk_i32 s14, 0x1f00
	v_mul_lo_u32 v163, v0, s14
	v_add_lshl_u32 v164, v163, v162, 1
	v_add_u32_e32 v165, 0x3e000, v164
	v_add_u32_e32 v166, 0x7c000, v164
	v_add_u32_e32 v167, 0xba000, v164
	v_add_u32_e32 v168, 0x1f0000, v164
	v_add_u32_e32 v169, 0x22e000, v164
	v_add_u32_e32 v170, 0x26c000, v164
	v_add_u32_e32 v171, 0x2aa000, v164
	s_cmp_eq_u32 s3, 2
	s_cbranch_scc0 .Lg1_fast_st
	s_mov_b32 s12, 0x3e000000
	v_pk_mul_f32 v[142:143], v[142:143], s[12:13] op_sel_hi:[1,0]
	v_pk_mul_f32 v[144:145], v[144:145], s[12:13] op_sel_hi:[1,0]
	v_pk_mul_f32 v[138:139], v[138:139], s[12:13] op_sel_hi:[1,0]
	v_pk_mul_f32 v[140:141], v[140:141], s[12:13] op_sel_hi:[1,0]
	v_pk_mul_f32 v[126:127], v[126:127], s[12:13] op_sel_hi:[1,0]
	v_pk_mul_f32 v[128:129], v[128:129], s[12:13] op_sel_hi:[1,0]
	v_pk_mul_f32 v[122:123], v[122:123], s[12:13] op_sel_hi:[1,0]
	v_pk_mul_f32 v[124:125], v[124:125], s[12:13] op_sel_hi:[1,0]
	v_pk_mul_f32 v[110:111], v[110:111], s[12:13] op_sel_hi:[1,0]
	v_pk_mul_f32 v[112:113], v[112:113], s[12:13] op_sel_hi:[1,0]
	v_pk_mul_f32 v[106:107], v[106:107], s[12:13] op_sel_hi:[1,0]
	v_pk_mul_f32 v[108:109], v[108:109], s[12:13] op_sel_hi:[1,0]
	v_pk_mul_f32 v[94:95], v[94:95], s[12:13] op_sel_hi:[1,0]
	v_pk_mul_f32 v[96:97], v[96:97], s[12:13] op_sel_hi:[1,0]
	v_pk_mul_f32 v[90:91], v[90:91], s[12:13] op_sel_hi:[1,0]
	v_pk_mul_f32 v[92:93], v[92:93], s[12:13] op_sel_hi:[1,0]
	v_pk_mul_f32 v[134:135], v[134:135], s[12:13] op_sel_hi:[1,0]
	v_pk_mul_f32 v[136:137], v[136:137], s[12:13] op_sel_hi:[1,0]
	v_pk_mul_f32 v[130:131], v[130:131], s[12:13] op_sel_hi:[1,0]
	v_pk_mul_f32 v[132:133], v[132:133], s[12:13] op_sel_hi:[1,0]
	v_pk_mul_f32 v[118:119], v[118:119], s[12:13] op_sel_hi:[1,0]
	v_pk_mul_f32 v[120:121], v[120:121], s[12:13] op_sel_hi:[1,0]
	v_pk_mul_f32 v[114:115], v[114:115], s[12:13] op_sel_hi:[1,0]
	v_pk_mul_f32 v[116:117], v[116:117], s[12:13] op_sel_hi:[1,0]
	v_pk_mul_f32 v[102:103], v[102:103], s[12:13] op_sel_hi:[1,0]
	v_pk_mul_f32 v[104:105], v[104:105], s[12:13] op_sel_hi:[1,0]
	v_pk_mul_f32 v[98:99], v[98:99], s[12:13] op_sel_hi:[1,0]
	v_pk_mul_f32 v[100:101], v[100:101], s[12:13] op_sel_hi:[1,0]
	v_pk_mul_f32 v[86:87], v[86:87], s[12:13] op_sel_hi:[1,0]
	v_pk_mul_f32 v[88:89], v[88:89], s[12:13] op_sel_hi:[1,0]
	v_pk_mul_f32 v[82:83], v[82:83], s[12:13] op_sel_hi:[1,0]
	v_pk_mul_f32 v[84:85], v[84:85], s[12:13] op_sel_hi:[1,0]
	v_pk_mul_f32 v[78:79], v[78:79], s[12:13] op_sel_hi:[1,0]
	v_pk_mul_f32 v[80:81], v[80:81], s[12:13] op_sel_hi:[1,0]
	v_pk_mul_f32 v[74:75], v[74:75], s[12:13] op_sel_hi:[1,0]
	v_pk_mul_f32 v[76:77], v[76:77], s[12:13] op_sel_hi:[1,0]
	v_pk_mul_f32 v[62:63], v[62:63], s[12:13] op_sel_hi:[1,0]
	v_pk_mul_f32 v[64:65], v[64:65], s[12:13] op_sel_hi:[1,0]
	v_pk_mul_f32 v[58:59], v[58:59], s[12:13] op_sel_hi:[1,0]
	v_pk_mul_f32 v[60:61], v[60:61], s[12:13] op_sel_hi:[1,0]
	v_pk_mul_f32 v[38:39], v[38:39], s[12:13] op_sel_hi:[1,0]
	v_pk_mul_f32 v[40:41], v[40:41], s[12:13] op_sel_hi:[1,0]
	v_pk_mul_f32 v[34:35], v[34:35], s[12:13] op_sel_hi:[1,0]
	v_pk_mul_f32 v[36:37], v[36:37], s[12:13] op_sel_hi:[1,0]
	v_pk_mul_f32 v[14:15], v[14:15], s[12:13] op_sel_hi:[1,0]
	v_pk_mul_f32 v[16:17], v[16:17], s[12:13] op_sel_hi:[1,0]
	v_pk_mul_f32 v[10:11], v[10:11], s[12:13] op_sel_hi:[1,0]
	v_pk_mul_f32 v[12:13], v[12:13], s[12:13] op_sel_hi:[1,0]
	v_pk_mul_f32 v[70:71], v[70:71], s[12:13] op_sel_hi:[1,0]
	v_pk_mul_f32 v[72:73], v[72:73], s[12:13] op_sel_hi:[1,0]
	v_pk_mul_f32 v[66:67], v[66:67], s[12:13] op_sel_hi:[1,0]
	v_pk_mul_f32 v[68:69], v[68:69], s[12:13] op_sel_hi:[1,0]
	v_pk_mul_f32 v[54:55], v[54:55], s[12:13] op_sel_hi:[1,0]
	v_pk_mul_f32 v[56:57], v[56:57], s[12:13] op_sel_hi:[1,0]
	v_pk_mul_f32 v[50:51], v[50:51], s[12:13] op_sel_hi:[1,0]
	v_pk_mul_f32 v[52:53], v[52:53], s[12:13] op_sel_hi:[1,0]
	v_pk_mul_f32 v[22:23], v[22:23], s[12:13] op_sel_hi:[1,0]
	v_pk_mul_f32 v[24:25], v[24:25], s[12:13] op_sel_hi:[1,0]
	v_pk_mul_f32 v[18:19], v[18:19], s[12:13] op_sel_hi:[1,0]
	v_pk_mul_f32 v[20:21], v[20:21], s[12:13] op_sel_hi:[1,0]
	v_pk_mul_f32 v[6:7], v[6:7], s[12:13] op_sel_hi:[1,0]
	v_pk_mul_f32 v[8:9], v[8:9], s[12:13] op_sel_hi:[1,0]
	v_pk_mul_f32 v[2:3], v[2:3], s[12:13] op_sel_hi:[1,0]
	v_pk_mul_f32 v[4:5], v[4:5], s[12:13] op_sel_hi:[1,0]
.Lg1_fast_st:
	v_cvt_pk_bf16_f32 v210, v142, v143
	v_cvt_pk_bf16_f32 v211, v144, v145
	v_cvt_pk_bf16_f32 v212, v138, v139
	v_cvt_pk_bf16_f32 v213, v140, v141
	global_store_dwordx4 v164, v[210:213], s[18:19]
	v_cvt_pk_bf16_f32 v214, v134, v135
	v_cvt_pk_bf16_f32 v215, v136, v137
	v_cvt_pk_bf16_f32 v216, v130, v131
	v_cvt_pk_bf16_f32 v217, v132, v133
	global_store_dwordx4 v164, v[214:217], s[18:19] offset:256
	v_cvt_pk_bf16_f32 v218, v126, v127
	v_cvt_pk_bf16_f32 v219, v128, v129
	v_cvt_pk_bf16_f32 v220, v122, v123
	v_cvt_pk_bf16_f32 v221, v124, v125
	global_store_dwordx4 v165, v[218:221], s[18:19]
	v_cvt_pk_bf16_f32 v222, v118, v119
	v_cvt_pk_bf16_f32 v223, v120, v121
	v_cvt_pk_bf16_f32 v224, v114, v115
	v_cvt_pk_bf16_f32 v225, v116, v117
	global_store_dwordx4 v165, v[222:225], s[18:19] offset:256
	v_cvt_pk_bf16_f32 v226, v110, v111
	v_cvt_pk_bf16_f32 v227, v112, v113
	v_cvt_pk_bf16_f32 v228, v106, v107
	v_cvt_pk_bf16_f32 v229, v108, v109
	global_store_dwordx4 v166, v[226:229], s[18:19]
	v_cvt_pk_bf16_f32 v230, v102, v103
	v_cvt_pk_bf16_f32 v231, v104, v105
	v_cvt_pk_bf16_f32 v232, v98, v99
	v_cvt_pk_bf16_f32 v233, v100, v101
	global_store_dwordx4 v166, v[230:233], s[18:19] offset:256
	v_cvt_pk_bf16_f32 v234, v94, v95
	v_cvt_pk_bf16_f32 v235, v96, v97
	v_cvt_pk_bf16_f32 v236, v90, v91
	v_cvt_pk_bf16_f32 v237, v92, v93
	global_store_dwordx4 v167, v[234:237], s[18:19]
	v_cvt_pk_bf16_f32 v238, v86, v87
	v_cvt_pk_bf16_f32 v239, v88, v89
	v_cvt_pk_bf16_f32 v240, v82, v83
	v_cvt_pk_bf16_f32 v241, v84, v85
	global_store_dwordx4 v167, v[238:241], s[18:19] offset:256
	v_cvt_pk_bf16_f32 v210, v78, v79
	v_cvt_pk_bf16_f32 v211, v80, v81
	v_cvt_pk_bf16_f32 v212, v74, v75
	v_cvt_pk_bf16_f32 v213, v76, v77
	global_store_dwordx4 v168, v[210:213], s[18:19]
	v_cvt_pk_bf16_f32 v214, v70, v71
	v_cvt_pk_bf16_f32 v215, v72, v73
	v_cvt_pk_bf16_f32 v216, v66, v67
	v_cvt_pk_bf16_f32 v217, v68, v69
	global_store_dwordx4 v168, v[214:217], s[18:19] offset:256
	v_cvt_pk_bf16_f32 v218, v62, v63
	v_cvt_pk_bf16_f32 v219, v64, v65
	v_cvt_pk_bf16_f32 v220, v58, v59
	v_cvt_pk_bf16_f32 v221, v60, v61
	global_store_dwordx4 v169, v[218:221], s[18:19]
	v_cvt_pk_bf16_f32 v222, v54, v55
	v_cvt_pk_bf16_f32 v223, v56, v57
	v_cvt_pk_bf16_f32 v224, v50, v51
	v_cvt_pk_bf16_f32 v225, v52, v53
	global_store_dwordx4 v169, v[222:225], s[18:19] offset:256
	v_cvt_pk_bf16_f32 v226, v38, v39
	v_cvt_pk_bf16_f32 v227, v40, v41
	v_cvt_pk_bf16_f32 v228, v34, v35
	v_cvt_pk_bf16_f32 v229, v36, v37
	global_store_dwordx4 v170, v[226:229], s[18:19]
	v_cvt_pk_bf16_f32 v230, v22, v23
	v_cvt_pk_bf16_f32 v231, v24, v25
	v_cvt_pk_bf16_f32 v232, v18, v19
	v_cvt_pk_bf16_f32 v233, v20, v21
	global_store_dwordx4 v170, v[230:233], s[18:19] offset:256
	v_cvt_pk_bf16_f32 v234, v14, v15
	v_cvt_pk_bf16_f32 v235, v16, v17
	v_cvt_pk_bf16_f32 v236, v10, v11
	v_cvt_pk_bf16_f32 v237, v12, v13
	global_store_dwordx4 v171, v[234:237], s[18:19]
	v_cvt_pk_bf16_f32 v238, v6, v7
	v_cvt_pk_bf16_f32 v239, v8, v9
	v_cvt_pk_bf16_f32 v240, v2, v3
	v_cvt_pk_bf16_f32 v241, v4, v5
	global_store_dwordx4 v171, v[238:241], s[18:19] offset:256
	s_branch .LBB0_963
